# NSA tile loop: drop 31 dead spill-lane read/writes per tile around the LDS-DMA issue
# speedup vs baseline: 1.0370x; 1.0370x over previous
; DI void nsa_unit(const Args& a, LAS unsigned char* lds, int b, int g, int jb) {
;     ...
;             if (pfw) { const int tp = __builtin_ctz(pfw); pfw &= pfw - 1u; NSA_DMA(true, tp, spf); spf = spf == 5 ? 0 : spf + 1; issued = true; }
;             else if (pfs) { const int tp = __builtin_ctz(pfs); pfs &= pfs - 1u; NSA_DMA(false, tp, spf); spf = spf == 5 ? 0 : spf + 1; issued = true; }
.LBB0_2028:
	v_readlane_b32 s37, v254, 12
	s_mov_b32 s5, s37
	s_lshl_b32 s4, s7, 16
	s_add_i32 s2, s74, s6
	v_lshl_add_u64 v[4:5], v[4:5], 0, s[4:5]
	s_mov_b32 m0, s2
	s_nop 0
	global_load_lds_dwordx4 v[4:5], off
	v_lshl_add_u64 v[4:5], v[4:5], 0, s[70:71]
	s_add_i32 m0, s2, 0x2000
	s_add_i32 s2, s33, 1
	global_load_lds_dwordx4 v[4:5], off
	s_cmp_lg_u32 s33, 5
	s_cselect_b32 s33, s2, 0
	s_mov_b64 s[4:5], -1
